# squared-ReLU epilogue: dropped redundant canonicalising self-max
# speedup vs baseline: 1.1160x; 1.0043x over previous
.Lnxk9_skip:
	v_lshlrev_b64 v[120:121], 13, v[118:119]
	s_movk_i32 s3, 0x1000
	v_lshl_add_u64 v[120:121], s[18:19], 0, v[120:121]
	v_cmp_gt_i32_e32 vcc, s3, v116
	v_ashrrev_i32_e32 v117, 31, v116
	s_and_saveexec_b64 s[30:31], vcc
	s_cbranch_execz .LBB0_144
	v_max_f32_e32 v128, 0, v156
	v_max_f32_e32 v129, 0, v157
	v_max_f32_e32 v130, 0, v158
	v_max_f32_e32 v131, 0, v159
	v_max_f32_e32 v136, 0, v148
	v_max_f32_e32 v137, 0, v149
	v_max_f32_e32 v138, 0, v150
	v_max_f32_e32 v139, 0, v151
	v_pk_mul_f32 v[128:129], v[128:129], v[128:129]
	v_pk_mul_f32 v[130:131], v[130:131], v[130:131]
	v_cvt_pk_f16_f32 v128, v128, v129
	v_cvt_pk_f16_f32 v129, v130, v131
	v_pk_mul_f32 v[130:131], v[136:137], v[136:137]
	v_pk_mul_f32 v[136:137], v[138:139], v[138:139]
	v_lshl_add_u64 v[122:123], v[116:117], 1, v[120:121]
	v_cvt_pk_f16_f32 v130, v130, v131
	v_cvt_pk_f16_f32 v131, v136, v137
	global_store_dwordx4 v[122:123], v[128:131], off
.LBB0_144:
	s_or_b64 exec, exec, s[30:31]
	v_or_b32_e32 v119, 32, v116
	v_cmp_gt_i32_e64 s[38:39], s3, v119
	s_and_saveexec_b64 s[30:31], s[38:39]
	s_cbranch_execz .LBB0_146
	v_lshl_add_u64 v[128:129], v[116:117], 1, v[120:121]
	v_max_f32_e32 v120, 0, v132
	v_max_f32_e32 v121, 0, v133
	v_max_f32_e32 v122, 0, v134
	v_max_f32_e32 v123, 0, v135
	v_max_f32_e32 v124, 0, v124
	v_max_f32_e32 v125, 0, v125
	v_max_f32_e32 v126, 0, v126
	v_max_f32_e32 v127, 0, v127
	v_pk_mul_f32 v[120:121], v[120:121], v[120:121]
	v_pk_mul_f32 v[122:123], v[122:123], v[122:123]
	v_cvt_pk_f16_f32 v120, v120, v121
	v_cvt_pk_f16_f32 v121, v122, v123
	v_pk_mul_f32 v[122:123], v[124:125], v[124:125]
	v_pk_mul_f32 v[124:125], v[126:127], v[126:127]
	v_cvt_pk_f16_f32 v122, v122, v123
	v_cvt_pk_f16_f32 v123, v124, v125
	global_store_dwordx4 v[128:129], v[120:123], off offset:64
.LBB0_146:
	s_or_b64 exec, exec, s[30:31]
	s_nop 0
	v_or_b32_e32 v120, 16, v118
	v_ashrrev_i32_e32 v121, 31, v120
	v_lshlrev_b64 v[120:121], 13, v[120:121]
	v_lshl_add_u64 v[120:121], s[18:19], 0, v[120:121]
	s_and_saveexec_b64 s[30:31], vcc
	s_cbranch_execz .LBB0_148
	v_max_f32_e32 v124, 0, v108
	v_max_f32_e32 v125, 0, v109
	v_max_f32_e32 v112, 0, v112
	v_max_f32_e32 v113, 0, v113
	v_max_f32_e32 v114, 0, v114
	v_max_f32_e32 v115, 0, v115
	v_max_f32_e32 v126, 0, v110
	v_max_f32_e32 v127, 0, v111
	v_pk_mul_f32 v[108:109], v[112:113], v[112:113]
	v_pk_mul_f32 v[110:111], v[114:115], v[114:115]
	v_cvt_pk_f16_f32 v108, v108, v109
	v_cvt_pk_f16_f32 v109, v110, v111
	v_pk_mul_f32 v[110:111], v[124:125], v[124:125]
	v_pk_mul_f32 v[112:113], v[126:127], v[126:127]
	v_lshl_add_u64 v[122:123], v[116:117], 1, v[120:121]
	v_cvt_pk_f16_f32 v110, v110, v111
	v_cvt_pk_f16_f32 v111, v112, v113
	global_store_dwordx4 v[122:123], v[108:111], off
.LBB0_148:
	s_or_b64 exec, exec, s[30:31]
	s_and_saveexec_b64 s[30:31], s[38:39]
	s_cbranch_execz .LBB0_150
	v_max_f32_e32 v110, 0, v100
	v_max_f32_e32 v111, 0, v101
	v_max_f32_e32 v104, 0, v104
	v_max_f32_e32 v105, 0, v105
	v_max_f32_e32 v106, 0, v106
	v_max_f32_e32 v107, 0, v107
	v_max_f32_e32 v112, 0, v102
	v_max_f32_e32 v113, 0, v103
	v_pk_mul_f32 v[100:101], v[104:105], v[104:105]
	v_pk_mul_f32 v[102:103], v[106:107], v[106:107]
	v_cvt_pk_f16_f32 v100, v100, v101
	v_cvt_pk_f16_f32 v101, v102, v103
	v_pk_mul_f32 v[102:103], v[110:111], v[110:111]
	v_pk_mul_f32 v[104:105], v[112:113], v[112:113]
	v_lshl_add_u64 v[108:109], v[116:117], 1, v[120:121]
	v_cvt_pk_f16_f32 v102, v102, v103
	v_cvt_pk_f16_f32 v103, v104, v105
	global_store_dwordx4 v[108:109], v[100:103], off offset:64
.LBB0_150:
	s_or_b64 exec, exec, s[30:31]
	s_nop 0
	v_or_b32_e32 v100, 32, v118
	v_ashrrev_i32_e32 v101, 31, v100
	v_lshlrev_b64 v[100:101], 13, v[100:101]
	v_lshl_add_u64 v[100:101], s[18:19], 0, v[100:101]
	s_and_saveexec_b64 s[30:31], vcc
	s_cbranch_execz .LBB0_152
	v_max_f32_e32 v104, 0, v92
	v_max_f32_e32 v105, 0, v93
	v_max_f32_e32 v96, 0, v96
	v_max_f32_e32 v97, 0, v97
	v_max_f32_e32 v98, 0, v98
	v_max_f32_e32 v99, 0, v99
	v_max_f32_e32 v106, 0, v94
	v_max_f32_e32 v107, 0, v95
	v_pk_mul_f32 v[92:93], v[96:97], v[96:97]
	v_pk_mul_f32 v[94:95], v[98:99], v[98:99]
	v_cvt_pk_f16_f32 v92, v92, v93
	v_cvt_pk_f16_f32 v93, v94, v95
	v_pk_mul_f32 v[94:95], v[104:105], v[104:105]
	v_pk_mul_f32 v[96:97], v[106:107], v[106:107]
	v_lshl_add_u64 v[102:103], v[116:117], 1, v[100:101]
	v_cvt_pk_f16_f32 v94, v94, v95
	v_cvt_pk_f16_f32 v95, v96, v97
	global_store_dwordx4 v[102:103], v[92:95], off
.LBB0_152:
	s_or_b64 exec, exec, s[30:31]
	s_and_saveexec_b64 s[30:31], s[38:39]
	s_cbranch_execz .LBB0_154
	v_max_f32_e32 v94, 0, v84
	v_max_f32_e32 v95, 0, v85
	v_max_f32_e32 v88, 0, v88
	v_max_f32_e32 v89, 0, v89
	v_max_f32_e32 v90, 0, v90
	v_max_f32_e32 v91, 0, v91
	v_max_f32_e32 v96, 0, v86
	v_max_f32_e32 v97, 0, v87
	v_pk_mul_f32 v[84:85], v[88:89], v[88:89]
	v_pk_mul_f32 v[86:87], v[90:91], v[90:91]
	v_cvt_pk_f16_f32 v84, v84, v85
	v_cvt_pk_f16_f32 v85, v86, v87
	v_pk_mul_f32 v[86:87], v[94:95], v[94:95]
	v_pk_mul_f32 v[88:89], v[96:97], v[96:97]
	v_lshl_add_u64 v[92:93], v[116:117], 1, v[100:101]
	v_cvt_pk_f16_f32 v86, v86, v87
	v_cvt_pk_f16_f32 v87, v88, v89
	global_store_dwordx4 v[92:93], v[84:87], off offset:64
.LBB0_154:
	s_or_b64 exec, exec, s[30:31]
	s_nop 0
	v_or_b32_e32 v84, 48, v118
	v_ashrrev_i32_e32 v85, 31, v84
	v_lshlrev_b64 v[84:85], 13, v[84:85]
	v_lshl_add_u64 v[84:85], s[18:19], 0, v[84:85]
	s_and_saveexec_b64 s[30:31], vcc
	s_cbranch_execz .LBB0_156
	v_max_f32_e32 v88, 0, v76
	v_max_f32_e32 v89, 0, v77
	v_max_f32_e32 v80, 0, v80
	v_max_f32_e32 v81, 0, v81
	v_max_f32_e32 v82, 0, v82
	v_max_f32_e32 v83, 0, v83
	v_max_f32_e32 v90, 0, v78
	v_max_f32_e32 v91, 0, v79
	v_pk_mul_f32 v[76:77], v[80:81], v[80:81]
	v_pk_mul_f32 v[78:79], v[82:83], v[82:83]
	v_cvt_pk_f16_f32 v76, v76, v77
	v_cvt_pk_f16_f32 v77, v78, v79
	v_pk_mul_f32 v[78:79], v[88:89], v[88:89]
	v_pk_mul_f32 v[80:81], v[90:91], v[90:91]
	v_lshl_add_u64 v[86:87], v[116:117], 1, v[84:85]
	v_cvt_pk_f16_f32 v78, v78, v79
	v_cvt_pk_f16_f32 v79, v80, v81
	global_store_dwordx4 v[86:87], v[76:79], off
.LBB0_156:
	s_or_b64 exec, exec, s[30:31]
	s_and_saveexec_b64 s[30:31], s[38:39]
	s_cbranch_execz .LBB0_158
	v_max_f32_e32 v78, 0, v68
	v_max_f32_e32 v79, 0, v69
	v_max_f32_e32 v72, 0, v72
	v_max_f32_e32 v73, 0, v73
	v_max_f32_e32 v74, 0, v74
	v_max_f32_e32 v75, 0, v75
	v_max_f32_e32 v80, 0, v70
	v_max_f32_e32 v81, 0, v71
	v_pk_mul_f32 v[68:69], v[72:73], v[72:73]
	v_pk_mul_f32 v[70:71], v[74:75], v[74:75]
	v_cvt_pk_f16_f32 v68, v68, v69
	v_cvt_pk_f16_f32 v69, v70, v71
	v_pk_mul_f32 v[70:71], v[78:79], v[78:79]
	v_pk_mul_f32 v[72:73], v[80:81], v[80:81]
	v_lshl_add_u64 v[76:77], v[116:117], 1, v[84:85]
	v_cvt_pk_f16_f32 v70, v70, v71
	v_cvt_pk_f16_f32 v71, v72, v73
	global_store_dwordx4 v[76:77], v[68:71], off offset:64
.LBB0_158:
	s_or_b64 exec, exec, s[30:31]
	s_nop 0
	v_or_b32_e32 v68, 64, v118
	v_ashrrev_i32_e32 v69, 31, v68
	v_lshlrev_b64 v[68:69], 13, v[68:69]
	v_lshl_add_u64 v[68:69], s[18:19], 0, v[68:69]
	s_and_saveexec_b64 s[30:31], vcc
	s_cbranch_execz .LBB0_160
	v_max_f32_e32 v72, 0, v60
	v_max_f32_e32 v73, 0, v61
	v_max_f32_e32 v64, 0, v64
	v_max_f32_e32 v65, 0, v65
	v_max_f32_e32 v66, 0, v66
	v_max_f32_e32 v67, 0, v67
	v_max_f32_e32 v74, 0, v62
	v_max_f32_e32 v75, 0, v63
	v_pk_mul_f32 v[60:61], v[64:65], v[64:65]
	v_pk_mul_f32 v[62:63], v[66:67], v[66:67]
	v_cvt_pk_f16_f32 v60, v60, v61
	v_cvt_pk_f16_f32 v61, v62, v63
	v_pk_mul_f32 v[62:63], v[72:73], v[72:73]
	v_pk_mul_f32 v[64:65], v[74:75], v[74:75]
	v_lshl_add_u64 v[70:71], v[116:117], 1, v[68:69]
	v_cvt_pk_f16_f32 v62, v62, v63
	v_cvt_pk_f16_f32 v63, v64, v65
	global_store_dwordx4 v[70:71], v[60:63], off
.LBB0_160:
	s_or_b64 exec, exec, s[30:31]
	s_and_saveexec_b64 s[30:31], s[38:39]
	s_cbranch_execz .LBB0_162
	v_max_f32_e32 v62, 0, v52
	v_max_f32_e32 v63, 0, v53
	v_max_f32_e32 v56, 0, v56
	v_max_f32_e32 v57, 0, v57
	v_max_f32_e32 v58, 0, v58
	v_max_f32_e32 v59, 0, v59
	v_max_f32_e32 v64, 0, v54
	v_max_f32_e32 v65, 0, v55
	v_pk_mul_f32 v[52:53], v[56:57], v[56:57]
	v_pk_mul_f32 v[54:55], v[58:59], v[58:59]
	v_cvt_pk_f16_f32 v52, v52, v53
	v_cvt_pk_f16_f32 v53, v54, v55
	v_pk_mul_f32 v[54:55], v[62:63], v[62:63]
	v_pk_mul_f32 v[56:57], v[64:65], v[64:65]
	v_lshl_add_u64 v[60:61], v[116:117], 1, v[68:69]
	v_cvt_pk_f16_f32 v54, v54, v55
	v_cvt_pk_f16_f32 v55, v56, v57
	global_store_dwordx4 v[60:61], v[52:55], off offset:64
.LBB0_162:
	s_or_b64 exec, exec, s[30:31]
	s_nop 0
	v_or_b32_e32 v52, 0x50, v118
	v_ashrrev_i32_e32 v53, 31, v52
	v_lshlrev_b64 v[52:53], 13, v[52:53]
	v_lshl_add_u64 v[52:53], s[18:19], 0, v[52:53]
	s_and_saveexec_b64 s[30:31], vcc
	s_cbranch_execz .LBB0_164
	v_max_f32_e32 v56, 0, v44
	v_max_f32_e32 v57, 0, v45
	v_max_f32_e32 v48, 0, v48
	v_max_f32_e32 v49, 0, v49
	v_max_f32_e32 v50, 0, v50
	v_max_f32_e32 v51, 0, v51
	v_max_f32_e32 v58, 0, v46
	v_max_f32_e32 v59, 0, v47
	v_pk_mul_f32 v[44:45], v[48:49], v[48:49]
	v_pk_mul_f32 v[46:47], v[50:51], v[50:51]
	v_cvt_pk_f16_f32 v44, v44, v45
	v_cvt_pk_f16_f32 v45, v46, v47
	v_pk_mul_f32 v[46:47], v[56:57], v[56:57]
	v_pk_mul_f32 v[48:49], v[58:59], v[58:59]
	v_lshl_add_u64 v[54:55], v[116:117], 1, v[52:53]
	v_cvt_pk_f16_f32 v46, v46, v47
	v_cvt_pk_f16_f32 v47, v48, v49
	global_store_dwordx4 v[54:55], v[44:47], off
.LBB0_164:
	s_or_b64 exec, exec, s[30:31]
	s_and_saveexec_b64 s[30:31], s[38:39]
	s_cbranch_execz .LBB0_166
	v_max_f32_e32 v46, 0, v36
	v_max_f32_e32 v47, 0, v37
	v_max_f32_e32 v40, 0, v40
	v_max_f32_e32 v41, 0, v41
	v_max_f32_e32 v42, 0, v42
	v_max_f32_e32 v43, 0, v43
	v_max_f32_e32 v48, 0, v38
	v_max_f32_e32 v49, 0, v39
	v_pk_mul_f32 v[36:37], v[40:41], v[40:41]
	v_pk_mul_f32 v[38:39], v[42:43], v[42:43]
	v_cvt_pk_f16_f32 v36, v36, v37
	v_cvt_pk_f16_f32 v37, v38, v39
	v_pk_mul_f32 v[38:39], v[46:47], v[46:47]
	v_pk_mul_f32 v[40:41], v[48:49], v[48:49]
	v_lshl_add_u64 v[44:45], v[116:117], 1, v[52:53]
	v_cvt_pk_f16_f32 v38, v38, v39
	v_cvt_pk_f16_f32 v39, v40, v41
	global_store_dwordx4 v[44:45], v[36:39], off offset:64
.LBB0_166:
	s_or_b64 exec, exec, s[30:31]
	s_nop 0
	v_or_b32_e32 v36, 0x60, v118
	v_ashrrev_i32_e32 v37, 31, v36
	v_lshlrev_b64 v[36:37], 13, v[36:37]
	v_lshl_add_u64 v[36:37], s[18:19], 0, v[36:37]
	s_and_saveexec_b64 s[30:31], vcc
	s_cbranch_execz .LBB0_168
	v_max_f32_e32 v40, 0, v26
	v_max_f32_e32 v41, 0, v27
	v_max_f32_e32 v30, 0, v30
	v_max_f32_e32 v31, 0, v31
	v_max_f32_e32 v32, 0, v32
	v_max_f32_e32 v33, 0, v33
	v_max_f32_e32 v42, 0, v28
	v_max_f32_e32 v43, 0, v29
	v_pk_mul_f32 v[26:27], v[30:31], v[30:31]
	v_pk_mul_f32 v[28:29], v[32:33], v[32:33]
	v_cvt_pk_f16_f32 v26, v26, v27
	v_cvt_pk_f16_f32 v27, v28, v29
	v_pk_mul_f32 v[28:29], v[40:41], v[40:41]
	v_pk_mul_f32 v[30:31], v[42:43], v[42:43]
	v_lshl_add_u64 v[38:39], v[116:117], 1, v[36:37]
	v_cvt_pk_f16_f32 v28, v28, v29
	v_cvt_pk_f16_f32 v29, v30, v31
	global_store_dwordx4 v[38:39], v[26:29], off
.LBB0_168:
	s_or_b64 exec, exec, s[30:31]
	s_and_saveexec_b64 s[30:31], s[38:39]
	s_cbranch_execz .LBB0_170
	v_max_f32_e32 v28, 0, v18
	v_max_f32_e32 v29, 0, v19
	v_max_f32_e32 v22, 0, v22
	v_max_f32_e32 v23, 0, v23
	v_max_f32_e32 v24, 0, v24
	v_max_f32_e32 v25, 0, v25
	v_max_f32_e32 v30, 0, v20
	v_max_f32_e32 v31, 0, v21
	v_pk_mul_f32 v[18:19], v[22:23], v[22:23]
	v_pk_mul_f32 v[20:21], v[24:25], v[24:25]
	v_cvt_pk_f16_f32 v18, v18, v19
	v_cvt_pk_f16_f32 v19, v20, v21
	v_pk_mul_f32 v[20:21], v[28:29], v[28:29]
	v_pk_mul_f32 v[22:23], v[30:31], v[30:31]
	v_lshl_add_u64 v[26:27], v[116:117], 1, v[36:37]
	v_cvt_pk_f16_f32 v20, v20, v21
	v_cvt_pk_f16_f32 v21, v22, v23
	global_store_dwordx4 v[26:27], v[18:21], off offset:64
.LBB0_170:
	s_or_b64 exec, exec, s[30:31]
	s_nop 0
	v_or_b32_e32 v18, 0x70, v118
	v_ashrrev_i32_e32 v19, 31, v18
	v_lshlrev_b64 v[18:19], 13, v[18:19]
	v_lshl_add_u64 v[18:19], s[18:19], 0, v[18:19]
	s_and_saveexec_b64 s[30:31], vcc
	s_cbranch_execz .LBB0_172
	v_max_f32_e32 v22, 0, v10
	v_max_f32_e32 v23, 0, v11
	v_max_f32_e32 v14, 0, v14
	v_max_f32_e32 v15, 0, v15
	v_max_f32_e32 v16, 0, v16
	v_max_f32_e32 v17, 0, v17
	v_max_f32_e32 v24, 0, v12
	v_max_f32_e32 v25, 0, v13
	v_pk_mul_f32 v[10:11], v[14:15], v[14:15]
	v_pk_mul_f32 v[12:13], v[16:17], v[16:17]
	v_cvt_pk_f16_f32 v10, v10, v11
	v_cvt_pk_f16_f32 v11, v12, v13
	v_pk_mul_f32 v[12:13], v[22:23], v[22:23]
	v_pk_mul_f32 v[14:15], v[24:25], v[24:25]
	v_lshl_add_u64 v[20:21], v[116:117], 1, v[18:19]
	v_cvt_pk_f16_f32 v12, v12, v13
	v_cvt_pk_f16_f32 v13, v14, v15
	global_store_dwordx4 v[20:21], v[10:13], off
.LBB0_172:
	s_or_b64 exec, exec, s[30:31]
	s_and_saveexec_b64 s[30:31], s[38:39]
	s_cbranch_execz .LBB0_174
	v_max_f32_e32 v12, 0, v2
	v_max_f32_e32 v13, 0, v3
	v_max_f32_e32 v6, 0, v6
	v_max_f32_e32 v7, 0, v7
	v_max_f32_e32 v8, 0, v8
	v_max_f32_e32 v9, 0, v9
	v_max_f32_e32 v14, 0, v4
	v_max_f32_e32 v15, 0, v5
	v_pk_mul_f32 v[2:3], v[6:7], v[6:7]
	v_pk_mul_f32 v[4:5], v[8:9], v[8:9]
	v_cvt_pk_f16_f32 v2, v2, v3
	v_cvt_pk_f16_f32 v3, v4, v5
	v_pk_mul_f32 v[4:5], v[12:13], v[12:13]
	v_pk_mul_f32 v[6:7], v[14:15], v[14:15]
	v_lshl_add_u64 v[10:11], v[116:117], 1, v[18:19]
	v_cvt_pk_f16_f32 v4, v4, v5
	v_cvt_pk_f16_f32 v5, v6, v7
	global_store_dwordx4 v[10:11], v[2:5], off offset:64
